# phase 2: workgroups 32-159 read the compress-GEMM input rows once at phase start (cache warm-up matched to the consumer XCD)
# baseline (speedup 1.0000x reference)
.LBB0_276:
	s_cmp_lt_i32 s28, 3
	s_cselect_b64 s[0:1], -1, 0
	s_cmp_gt_i32 s29, 2
	s_cselect_b64 s[2:3], -1, 0
	s_and_b64 s[0:1], s[0:1], s[2:3]
	s_andn2_b64 vcc, exec, s[0:1]
	s_cbranch_vccnz .LBB0_445
	s_cmpk_lt_i32 s30, 0xc0
	s_cselect_b64 s[0:1], -1, 0
	s_cmpk_lt_i32 s16, 0x20
	s_cselect_b64 s[2:3], -1, 0
	s_or_b64 s[0:1], s[2:3], s[0:1]
	v_mov_b32_e32 v0, v200
	s_and_b64 vcc, exec, s[0:1]
	s_cbranch_vccnz .LBB0_327
	s_cmpk_gt_i32 s16, 0x9f
	s_cbranch_scc1 .Lcmp_touch_done
	s_sub_i32 s0, s16, 32
	s_and_b32 s1, s0, 7
	s_lshr_b32 s0, s0, 3
	s_lshl_b32 s0, s0, 9
	v_add_u32_e32 v1, s0, v200
	v_lshrrev_b32_e32 v2, 12, v1
	v_lshl_add_u32 v2, v2, 3, s1
	v_and_b32_e32 v1, 0xfff, v1
	v_lshl_add_u32 v1, v2, 12, v1
	v_mul_u32_u24_e32 v2, 0xc00, v1
	v_mov_b32_e32 v3, 0
	s_add_u32 s2, s26, 0xe200600
	s_addc_u32 s3, s27, 0
	v_lshl_add_u64 v[2:3], s[2:3], 0, v[2:3]
	global_load_dword v250, v[2:3], off
	global_load_dword v251, v[2:3], off offset:128
.Lcmp_touch_done:
	v_readlane_b32 s0, v254, 3
	s_add_i32 s0, s0, 0xffffc000
	s_nop 0
	v_add_u32_e32 v4, s0, v0
	s_lshl_b32 s0, s30, 9
	s_add_i32 s8, s0, 0xffffc000
	s_movk_i32 s0, 0x3fff
	v_cmp_lt_i32_e64 s[2:3], s0, v4
	s_movk_i32 s0, 0x4000
	v_cmp_gt_i32_e32 vcc, s0, v4
	v_ashrrev_i32_e32 v5, 31, v4
	s_and_saveexec_b64 s[10:11], vcc
	s_cbranch_execz .LBB0_285
	v_lshlrev_b64 v[0:1], 11, v[4:5]
	s_ashr_i32 s9, s8, 31
	v_lshl_add_u64 v[0:1], s[26:27], 0, v[0:1]
	s_mov_b64 s[4:5], 0x400000
	v_lshl_add_u64 v[6:7], v[0:1], 0, s[4:5]
	s_lshl_b64 s[12:13], s[8:9], 11
	s_waitcnt lgkmcnt(0)
	v_lshl_add_u64 v[8:9], v[4:5], 2, s[74:75]
	s_lshl_b64 s[14:15], s[8:9], 2
	s_mov_b64 s[18:19], 0
	v_mov_b32_e32 v11, 0
	s_mov_b64 s[20:21], 0x3fff
	s_mov_b32 s4, 0
	v_mov_b64_e32 v[12:13], v[4:5]
	s_branch .LBB0_281
